# v3 plus: K-loops of the meta-row (16-row) items double-buffered in gemm1, gemm2, gemm3 and gemm3's down-projection tail (next step's 17 loads in flight under the current 16 MFMAs)
# baseline (speedup 1.0000x reference)
; #define SCHED __builtin_amdgcn_sched_barrier(0)
; template <class Epi>
; DEV void skinny_item(LAS unsigned char* lds, const bf16_t* __restrict__ A, int lda, const bf16_t* __restrict__ B, int ldb, int K, int mb, int pn, const Epi& epi) {
;     ...
;     const int nsteps = K >> 5;
; #pragma unroll 1
;     for (int st = wid; st < nsteps; st += 8) {
;         const int k0 = st * 32;
;         const bf16x8 a = *(const bf16x8*)(ap + k0);
;         bf16x8 b[16];
; #pragma unroll
;         for (int nb = 0; nb < 16; ++nb) b[nb] = *(const bf16x8*)(bp + nb * b16 + k0);
;         SCHED;
; #pragma unroll
;         for (int nb = 0; nb < 16; ++nb) acc[nb] = __builtin_amdgcn_mfma_f32_16x16x32_bf16(b[nb], a, acc[nb], 0, 0, 0);
;         SCHED;
;     }
.LBB0_420:
	s_movk_i32 s101, 3
	v_ashrrev_i32_e32 v69, 31, v68
	v_lshlrev_b64 v[74:75], 1, v[68:69]
	v_lshl_add_u64 v[138:139], v[66:67], 0, v[74:75]
	v_add_co_u32_e32 v82, vcc, s10, v138
	v_lshl_add_u64 v[76:77], v[64:65], 0, v[74:75]
	s_nop 0
	v_addc_co_u32_e32 v83, vcc, 0, v139, vcc
	v_add_co_u32_e32 v86, vcc, s11, v138
	global_load_dwordx4 v[74:77], v[76:77], off
	s_nop 0
	global_load_dwordx4 v[78:81], v[138:139], off
	v_addc_co_u32_e32 v87, vcc, 0, v139, vcc
	v_add_co_u32_e32 v90, vcc, s12, v138
	global_load_dwordx4 v[82:85], v[82:83], off
	s_nop 0
	global_load_dwordx4 v[86:89], v[86:87], off
	v_addc_co_u32_e32 v91, vcc, 0, v139, vcc
	v_add_co_u32_e32 v94, vcc, s59, v138
	s_nop 1
	v_addc_co_u32_e32 v95, vcc, 0, v139, vcc
	v_add_co_u32_e32 v98, vcc, s13, v138
	global_load_dwordx4 v[90:93], v[90:91], off
	s_nop 0
	global_load_dwordx4 v[94:97], v[94:95], off
	v_addc_co_u32_e32 v99, vcc, 0, v139, vcc
	v_add_co_u32_e32 v102, vcc, s14, v138
	s_nop 1
	v_addc_co_u32_e32 v103, vcc, 0, v139, vcc
	v_add_co_u32_e32 v106, vcc, s15, v138
	global_load_dwordx4 v[98:101], v[98:99], off
	s_nop 0
	global_load_dwordx4 v[102:105], v[102:103], off
	v_addc_co_u32_e32 v107, vcc, 0, v139, vcc
	v_add_co_u32_e32 v110, vcc, s16, v138
	s_nop 1
	v_addc_co_u32_e32 v111, vcc, 0, v139, vcc
	v_add_co_u32_e32 v114, vcc, s17, v138
	global_load_dwordx4 v[106:109], v[106:107], off
	s_nop 0
	global_load_dwordx4 v[110:113], v[110:111], off
	v_addc_co_u32_e32 v115, vcc, 0, v139, vcc
	v_add_co_u32_e32 v118, vcc, s18, v138
	s_nop 1
	v_addc_co_u32_e32 v119, vcc, 0, v139, vcc
	v_add_co_u32_e32 v122, vcc, s19, v138
	global_load_dwordx4 v[114:117], v[114:115], off
	s_nop 0
	global_load_dwordx4 v[118:121], v[118:119], off
	v_addc_co_u32_e32 v123, vcc, 0, v139, vcc
	v_add_co_u32_e32 v126, vcc, s20, v138
	s_nop 1
	v_addc_co_u32_e32 v127, vcc, 0, v139, vcc
	v_add_co_u32_e32 v130, vcc, s21, v138
	global_load_dwordx4 v[122:125], v[122:123], off
	s_nop 0
	global_load_dwordx4 v[126:129], v[126:127], off
	v_addc_co_u32_e32 v131, vcc, 0, v139, vcc
	v_add_co_u32_e32 v134, vcc, s22, v138
	s_nop 1
	v_addc_co_u32_e32 v135, vcc, 0, v139, vcc
	v_add_co_u32_e32 v138, vcc, s23, v138
	global_load_dwordx4 v[130:133], v[130:131], off
	s_nop 0
	global_load_dwordx4 v[134:137], v[134:135], off
	v_addc_co_u32_e32 v139, vcc, 0, v139, vcc
	global_load_dwordx4 v[138:141], v[138:139], off
.Lsk_loop_420:
	s_cmp_eq_u32 s101, 0
	s_cbranch_scc1 .Lsk_lastA_420
	s_sub_u32 s101, s101, 1
	v_add_u32_e32 v68, 0x100, v68
	v_ashrrev_i32_e32 v69, 31, v68
	v_lshlrev_b64 v[142:143], 1, v[68:69]
	v_lshl_add_u64 v[232:233], v[66:67], 0, v[142:143]
	v_add_co_u32_e32 v150, vcc, s10, v232
	v_lshl_add_u64 v[144:145], v[64:65], 0, v[142:143]
	s_nop 0
	v_addc_co_u32_e32 v151, vcc, 0, v233, vcc
	v_add_co_u32_e32 v154, vcc, s11, v232
	global_load_dwordx4 v[142:145], v[144:145], off
	s_nop 0
	global_load_dwordx4 v[146:149], v[232:233], off
	v_addc_co_u32_e32 v155, vcc, 0, v233, vcc
	v_add_co_u32_e32 v158, vcc, s12, v232
	global_load_dwordx4 v[150:153], v[150:151], off
	s_nop 0
	global_load_dwordx4 v[154:157], v[154:155], off
	v_addc_co_u32_e32 v159, vcc, 0, v233, vcc
	v_add_co_u32_e32 v162, vcc, s59, v232
	s_nop 1
	v_addc_co_u32_e32 v163, vcc, 0, v233, vcc
	v_add_co_u32_e32 v166, vcc, s13, v232
	global_load_dwordx4 v[158:161], v[158:159], off
	s_nop 0
	global_load_dwordx4 v[162:165], v[162:163], off
	v_addc_co_u32_e32 v167, vcc, 0, v233, vcc
	v_add_co_u32_e32 v170, vcc, s14, v232
	s_nop 1
	v_addc_co_u32_e32 v171, vcc, 0, v233, vcc
	v_add_co_u32_e32 v174, vcc, s15, v232
	global_load_dwordx4 v[166:169], v[166:167], off
	s_nop 0
	global_load_dwordx4 v[170:173], v[170:171], off
	v_addc_co_u32_e32 v175, vcc, 0, v233, vcc
	v_add_co_u32_e32 v178, vcc, s16, v232
	s_nop 1
	v_addc_co_u32_e32 v179, vcc, 0, v233, vcc
	v_add_co_u32_e32 v182, vcc, s17, v232
	global_load_dwordx4 v[174:177], v[174:175], off
	s_nop 0
	global_load_dwordx4 v[178:181], v[178:179], off
	v_addc_co_u32_e32 v183, vcc, 0, v233, vcc
	v_add_co_u32_e32 v212, vcc, s18, v232
	s_nop 1
	v_addc_co_u32_e32 v213, vcc, 0, v233, vcc
	v_add_co_u32_e32 v216, vcc, s19, v232
	global_load_dwordx4 v[182:185], v[182:183], off
	s_nop 0
	global_load_dwordx4 v[212:215], v[212:213], off
	v_addc_co_u32_e32 v217, vcc, 0, v233, vcc
	v_add_co_u32_e32 v220, vcc, s20, v232
	s_nop 1
	v_addc_co_u32_e32 v221, vcc, 0, v233, vcc
	v_add_co_u32_e32 v224, vcc, s21, v232
	global_load_dwordx4 v[216:219], v[216:217], off
	s_nop 0
	global_load_dwordx4 v[220:223], v[220:221], off
	v_addc_co_u32_e32 v225, vcc, 0, v233, vcc
	v_add_co_u32_e32 v228, vcc, s22, v232
	s_nop 1
	v_addc_co_u32_e32 v229, vcc, 0, v233, vcc
	v_add_co_u32_e32 v232, vcc, s23, v232
	global_load_dwordx4 v[224:227], v[224:225], off
	s_nop 0
	global_load_dwordx4 v[228:231], v[228:229], off
	v_addc_co_u32_e32 v233, vcc, 0, v233, vcc
	global_load_dwordx4 v[232:235], v[232:233], off
	s_waitcnt vmcnt(32)
	v_mfma_f32_16x16x32_bf16 v[60:63], v[78:81], v[74:77], v[60:63]
	s_waitcnt vmcnt(31)
	v_mfma_f32_16x16x32_bf16 v[56:59], v[82:85], v[74:77], v[56:59]
	s_waitcnt vmcnt(30)
	v_mfma_f32_16x16x32_bf16 v[52:55], v[86:89], v[74:77], v[52:55]
	s_waitcnt vmcnt(29)
	v_mfma_f32_16x16x32_bf16 v[48:51], v[90:93], v[74:77], v[48:51]
	s_waitcnt vmcnt(28)
	v_mfma_f32_16x16x32_bf16 v[44:47], v[94:97], v[74:77], v[44:47]
	s_waitcnt vmcnt(27)
	v_mfma_f32_16x16x32_bf16 v[40:43], v[98:101], v[74:77], v[40:43]
	s_waitcnt vmcnt(26)
	v_mfma_f32_16x16x32_bf16 v[36:39], v[102:105], v[74:77], v[36:39]
	s_waitcnt vmcnt(25)
	v_mfma_f32_16x16x32_bf16 v[32:35], v[106:109], v[74:77], v[32:35]
	s_waitcnt vmcnt(24)
	v_mfma_f32_16x16x32_bf16 v[28:31], v[110:113], v[74:77], v[28:31]
	s_waitcnt vmcnt(23)
	v_mfma_f32_16x16x32_bf16 v[24:27], v[114:117], v[74:77], v[24:27]
	s_waitcnt vmcnt(22)
	v_mfma_f32_16x16x32_bf16 v[20:23], v[118:121], v[74:77], v[20:23]
	s_waitcnt vmcnt(21)
	v_mfma_f32_16x16x32_bf16 v[16:19], v[122:125], v[74:77], v[16:19]
	s_waitcnt vmcnt(20)
	v_mfma_f32_16x16x32_bf16 v[12:15], v[126:129], v[74:77], v[12:15]
	s_waitcnt vmcnt(19)
	v_mfma_f32_16x16x32_bf16 v[8:11], v[130:133], v[74:77], v[8:11]
	s_waitcnt vmcnt(18)
	v_mfma_f32_16x16x32_bf16 v[4:7], v[134:137], v[74:77], v[4:7]
	s_waitcnt vmcnt(17)
	v_mfma_f32_16x16x32_bf16 v[0:3], v[138:141], v[74:77], v[0:3]
	s_cmp_eq_u32 s101, 0
	s_cbranch_scc1 .Lsk_lastB_420
; #define SCHED __builtin_amdgcn_sched_barrier(0)
; template <class Epi>
; DEV void skinny_item(LAS unsigned char* lds, const bf16_t* __restrict__ A, int lda, const bf16_t* __restrict__ B, int ldb, int K, int mb, int pn, const Epi& epi) {
;     ...
; #pragma unroll 1
;     for (int st = wid; st < nsteps; st += 8) {
;         const int k0 = st * 32;
;         const bf16x8 a = *(const bf16x8*)(ap + k0);
;         bf16x8 b[16];
; #pragma unroll
;         for (int nb = 0; nb < 16; ++nb) b[nb] = *(const bf16x8*)(bp + nb * b16 + k0);
;         SCHED;
; #pragma unroll
;         for (int nb = 0; nb < 16; ++nb) acc[nb] = __builtin_amdgcn_mfma_f32_16x16x32_bf16(b[nb], a, acc[nb], 0, 0, 0);
;         SCHED;
;     }
	s_sub_u32 s101, s101, 1
	v_add_u32_e32 v68, 0x100, v68
	v_ashrrev_i32_e32 v69, 31, v68
	v_lshlrev_b64 v[74:75], 1, v[68:69]
	v_lshl_add_u64 v[138:139], v[66:67], 0, v[74:75]
	v_add_co_u32_e32 v82, vcc, s10, v138
	v_lshl_add_u64 v[76:77], v[64:65], 0, v[74:75]
	s_nop 0
	v_addc_co_u32_e32 v83, vcc, 0, v139, vcc
	v_add_co_u32_e32 v86, vcc, s11, v138
	global_load_dwordx4 v[74:77], v[76:77], off
	s_nop 0
	global_load_dwordx4 v[78:81], v[138:139], off
	v_addc_co_u32_e32 v87, vcc, 0, v139, vcc
	v_add_co_u32_e32 v90, vcc, s12, v138
	global_load_dwordx4 v[82:85], v[82:83], off
	s_nop 0
	global_load_dwordx4 v[86:89], v[86:87], off
	v_addc_co_u32_e32 v91, vcc, 0, v139, vcc
	v_add_co_u32_e32 v94, vcc, s59, v138
	s_nop 1
	v_addc_co_u32_e32 v95, vcc, 0, v139, vcc
	v_add_co_u32_e32 v98, vcc, s13, v138
	global_load_dwordx4 v[90:93], v[90:91], off
	s_nop 0
	global_load_dwordx4 v[94:97], v[94:95], off
	v_addc_co_u32_e32 v99, vcc, 0, v139, vcc
	v_add_co_u32_e32 v102, vcc, s14, v138
	s_nop 1
	v_addc_co_u32_e32 v103, vcc, 0, v139, vcc
	v_add_co_u32_e32 v106, vcc, s15, v138
	global_load_dwordx4 v[98:101], v[98:99], off
	s_nop 0
	global_load_dwordx4 v[102:105], v[102:103], off
	v_addc_co_u32_e32 v107, vcc, 0, v139, vcc
	v_add_co_u32_e32 v110, vcc, s16, v138
	s_nop 1
	v_addc_co_u32_e32 v111, vcc, 0, v139, vcc
	v_add_co_u32_e32 v114, vcc, s17, v138
	global_load_dwordx4 v[106:109], v[106:107], off
	s_nop 0
	global_load_dwordx4 v[110:113], v[110:111], off
	v_addc_co_u32_e32 v115, vcc, 0, v139, vcc
	v_add_co_u32_e32 v118, vcc, s18, v138
	s_nop 1
	v_addc_co_u32_e32 v119, vcc, 0, v139, vcc
	v_add_co_u32_e32 v122, vcc, s19, v138
	global_load_dwordx4 v[114:117], v[114:115], off
	s_nop 0
	global_load_dwordx4 v[118:121], v[118:119], off
	v_addc_co_u32_e32 v123, vcc, 0, v139, vcc
	v_add_co_u32_e32 v126, vcc, s20, v138
	s_nop 1
	v_addc_co_u32_e32 v127, vcc, 0, v139, vcc
	v_add_co_u32_e32 v130, vcc, s21, v138
	global_load_dwordx4 v[122:125], v[122:123], off
	s_nop 0
	global_load_dwordx4 v[126:129], v[126:127], off
	v_addc_co_u32_e32 v131, vcc, 0, v139, vcc
	v_add_co_u32_e32 v134, vcc, s22, v138
	s_nop 1
	v_addc_co_u32_e32 v135, vcc, 0, v139, vcc
	v_add_co_u32_e32 v138, vcc, s23, v138
	global_load_dwordx4 v[130:133], v[130:131], off
	s_nop 0
	global_load_dwordx4 v[134:137], v[134:135], off
	v_addc_co_u32_e32 v139, vcc, 0, v139, vcc
	global_load_dwordx4 v[138:141], v[138:139], off
	s_waitcnt vmcnt(32)
	v_mfma_f32_16x16x32_bf16 v[60:63], v[146:149], v[142:145], v[60:63]
	s_waitcnt vmcnt(31)
	v_mfma_f32_16x16x32_bf16 v[56:59], v[150:153], v[142:145], v[56:59]
	s_waitcnt vmcnt(30)
	v_mfma_f32_16x16x32_bf16 v[52:55], v[154:157], v[142:145], v[52:55]
	s_waitcnt vmcnt(29)
	v_mfma_f32_16x16x32_bf16 v[48:51], v[158:161], v[142:145], v[48:51]
	s_waitcnt vmcnt(28)
	v_mfma_f32_16x16x32_bf16 v[44:47], v[162:165], v[142:145], v[44:47]
	s_waitcnt vmcnt(27)
	v_mfma_f32_16x16x32_bf16 v[40:43], v[166:169], v[142:145], v[40:43]
	s_waitcnt vmcnt(26)
	v_mfma_f32_16x16x32_bf16 v[36:39], v[170:173], v[142:145], v[36:39]
	s_waitcnt vmcnt(25)
	v_mfma_f32_16x16x32_bf16 v[32:35], v[174:177], v[142:145], v[32:35]
	s_waitcnt vmcnt(24)
	v_mfma_f32_16x16x32_bf16 v[28:31], v[178:181], v[142:145], v[28:31]
	s_waitcnt vmcnt(23)
	v_mfma_f32_16x16x32_bf16 v[24:27], v[182:185], v[142:145], v[24:27]
	s_waitcnt vmcnt(22)
	v_mfma_f32_16x16x32_bf16 v[20:23], v[212:215], v[142:145], v[20:23]
	s_waitcnt vmcnt(21)
	v_mfma_f32_16x16x32_bf16 v[16:19], v[216:219], v[142:145], v[16:19]
	s_waitcnt vmcnt(20)
	v_mfma_f32_16x16x32_bf16 v[12:15], v[220:223], v[142:145], v[12:15]
	s_waitcnt vmcnt(19)
	v_mfma_f32_16x16x32_bf16 v[8:11], v[224:227], v[142:145], v[8:11]
	s_waitcnt vmcnt(18)
	v_mfma_f32_16x16x32_bf16 v[4:7], v[228:231], v[142:145], v[4:7]
	s_waitcnt vmcnt(17)
	v_mfma_f32_16x16x32_bf16 v[0:3], v[232:235], v[142:145], v[0:3]
	s_branch .Lsk_loop_420

; #define LAS __attribute__((address_space(3)))
; DEV unsigned cvt_pk_bf16(float lo, float hi) { unsigned r; asm("v_cvt_pk_bf16_f32 %0, %1, %2" : "=v"(r) : "v"(lo), "v"(hi)); return r; }
; DEV float row_rs(const float* ss, int row) { const f32x4 s4 = *(const f32x4*)(ss + (size_t)row * 4); return rsqrtf(((s4[0] + s4[1]) + (s4[2] + s4[3])) * (1.0f / 1024.0f) + EPS); }
; DEV void skinny_reduce(LAS unsigned char* lds, int wid, int lane, const f32x4 (&acc)[16], f32x4& a0, f32x4& a1) {
; #pragma unroll
;     for (int nb = 0; nb < 16; ++nb) *(LAS f32x4*)(lds + ((wid * 16 + nb) * 64 + lane) * 16) = acc[nb];
;     __syncthreads();
;     a0 = (f32x4){0.f, 0.f, 0.f, 0.f}; a1 = a0;
; #pragma unroll
;     for (int w = 0; w < 8; ++w) { a0 += *(const LAS f32x4*)(lds + ((w * 16 + 2 * wid) * 64 + lane) * 16); a1 += *(const LAS f32x4*)(lds + ((w * 16 + 2 * wid + 1) * 64 + lane) * 16); }
;     __syncthreads();
; }
;     DEV void skinny(f32x4 a0, f32x4 a1, int mb, int pn, LAS unsigned char*) const {
;         EPI_IDS
;         const int row = TX + mb * 16 + fr;
;         const float rs = row_rs(ss, row);
;         const f32x4 v0 = a0 * rs, v1 = a1 * rs;
;         bf16_t* zp = z + (size_t)row * NZ + pn * 256 + wid * 32 + fq * 4;
;         *(u32x2*)zp = (u32x2){cvt_pk_bf16(v0[0], v0[1]), cvt_pk_bf16(v0[2], v0[3])};
;         *(u32x2*)(zp + 16) = (u32x2){cvt_pk_bf16(v1[0], v1[1]), cvt_pk_bf16(v1[2], v1[3])};
;         if (pn == 6) publish_fenced(tid);
;     }
.Lsk_done_420:
	s_or_b64 exec, exec, s[36:37]
.LBB0_422:
	s_or_b64 exec, exec, s[8:9]
	v_lshlrev_b32_e32 v65, 4, v71
	v_lshlrev_b32_e32 v64, 14, v70
	v_and_b32_e32 v65, 0x3f0, v65
	v_add3_u32 v64, 0, v64, v65
	ds_write_b128 v64, v[60:63]
	ds_write_b128 v64, v[56:59] offset:1024
	ds_write_b128 v64, v[52:55] offset:2048
	ds_write_b128 v64, v[48:51] offset:3072
	ds_write_b128 v64, v[44:47] offset:4096
	ds_write_b128 v64, v[40:43] offset:5120
	ds_write_b128 v64, v[36:39] offset:6144
	ds_write_b128 v64, v[32:35] offset:7168
	ds_write_b128 v64, v[28:31] offset:8192
	ds_write_b128 v64, v[24:27] offset:9216
	ds_write_b128 v64, v[20:23] offset:10240
	ds_write_b128 v64, v[16:19] offset:11264
	ds_write_b128 v64, v[12:15] offset:12288
	ds_write_b128 v64, v[8:11] offset:13312
	ds_write_b128 v64, v[4:7] offset:14336
	ds_write_b128 v64, v[0:3] offset:15360
	v_lshlrev_b32_e32 v0, 11, v70
	v_add3_u32 v0, 0, v0, v65
	v_add_u32_e32 v1, 0x10000, v0
	v_add_u32_e32 v38, 0x10400, v0
	s_waitcnt lgkmcnt(0)
	s_barrier
	ds_read_b128 v[2:5], v0
	ds_read_b128 v[6:9], v0 offset:1024
	ds_read_b128 v[10:13], v0 offset:16384
	ds_read_b128 v[14:17], v0 offset:17408
	ds_read_b128 v[18:21], v0 offset:32768
	ds_read_b128 v[22:25], v0 offset:33792
	ds_read_b128 v[26:29], v0 offset:49152
	ds_read_b128 v[30:33], v0 offset:50176
	ds_read_b128 v[34:37], v1
	ds_read_b128 v[38:41], v38
	v_add_u32_e32 v1, 0x14000, v0
	v_add_u32_e32 v46, 0x14400, v0
	ds_read_b128 v[42:45], v1
	ds_read_b128 v[46:49], v46
	v_add_u32_e32 v1, 0x18000, v0
	v_add_u32_e32 v54, 0x18400, v0
	ds_read_b128 v[50:53], v1
	ds_read_b128 v[54:57], v54
	v_add_u32_e32 v1, 0x1c000, v0
	v_add_u32_e32 v0, 0x1c400, v0
	ds_read_b128 v[58:61], v1
	ds_read_b128 v[62:65], v0
	v_mov_b32_e32 v0, v188
	v_readlane_b32 s4, v251, 46
	s_waitcnt lgkmcnt(0)
	s_barrier
	v_readlane_b32 s8, v251, 15
	v_and_or_b32 v1, v0, 15, s4
	v_lshlrev_b32_e32 v66, 4, v1
	v_readlane_b32 s9, v251, 16
	v_pk_add_f32 v[2:3], v[2:3], 0 op_sel_hi:[1,0]
	v_pk_add_f32 v[4:5], v[4:5], 0 op_sel_hi:[1,0]
	v_pk_add_f32 v[2:3], v[2:3], v[10:11]
	v_pk_add_f32 v[8:9], v[8:9], 0 op_sel_hi:[1,0]
	v_pk_add_f32 v[6:7], v[6:7], 0 op_sel_hi:[1,0]
	global_load_dwordx4 v[66:69], v66, s[8:9]
	v_pk_add_f32 v[4:5], v[4:5], v[12:13]
	v_pk_add_f32 v[8:9], v[8:9], v[16:17]
	v_pk_add_f32 v[6:7], v[6:7], v[14:15]
	v_pk_add_f32 v[4:5], v[4:5], v[20:21]
	v_pk_add_f32 v[2:3], v[2:3], v[18:19]
	v_pk_add_f32 v[8:9], v[8:9], v[24:25]
	v_pk_add_f32 v[6:7], v[6:7], v[22:23]
	v_pk_add_f32 v[4:5], v[4:5], v[28:29]
	v_pk_add_f32 v[2:3], v[2:3], v[26:27]
	v_pk_add_f32 v[8:9], v[8:9], v[32:33]
	v_pk_add_f32 v[6:7], v[6:7], v[30:31]
	v_pk_add_f32 v[4:5], v[4:5], v[36:37]
	v_pk_add_f32 v[2:3], v[2:3], v[34:35]
	v_pk_add_f32 v[8:9], v[8:9], v[40:41]
	v_pk_add_f32 v[6:7], v[6:7], v[38:39]
	v_pk_add_f32 v[4:5], v[4:5], v[44:45]
	v_pk_add_f32 v[2:3], v[2:3], v[42:43]
	v_pk_add_f32 v[8:9], v[8:9], v[48:49]
	v_pk_add_f32 v[6:7], v[6:7], v[46:47]
	v_pk_add_f32 v[4:5], v[4:5], v[52:53]
	v_pk_add_f32 v[2:3], v[2:3], v[50:51]
	v_pk_add_f32 v[8:9], v[8:9], v[56:57]
	v_pk_add_f32 v[6:7], v[6:7], v[54:55]
	v_lshlrev_b32_e32 v194, 12, v1
	v_readlane_b32 s8, v251, 48
	v_ashrrev_i32_e32 v1, 1, v0
	v_pk_add_f32 v[4:5], v[4:5], v[60:61]
	v_pk_add_f32 v[2:3], v[2:3], v[58:59]
	v_pk_add_f32 v[8:9], v[8:9], v[64:65]
	v_pk_add_f32 v[6:7], v[6:7], v[62:63]
	v_readlane_b32 s9, v251, 49
	v_and_b32_e32 v12, 0xffffffe0, v1
	v_ashrrev_i32_e32 v13, 31, v12
	v_lshrrev_b32_e32 v1, 1, v0
	s_waitcnt vmcnt(0)
	v_mov_b32_e32 v10, v67
	v_mov_b32_e32 v11, v68
	v_mov_b32_e32 v67, v69
	v_pk_add_f32 v[10:11], v[10:11], v[66:67]
	s_nop 0
	v_add_f32_e32 v10, v10, v11
	v_fmamk_f32 v10, v10, 0x3a800000, v189
	v_mul_f32_e32 v11, 0x4b800000, v10
	v_cmp_gt_f32_e32 vcc, s24, v10
	s_nop 1
	v_cndmask_b32_e32 v10, v10, v11, vcc
	v_rsq_f32_e32 v10, v10
	s_nop 0
	v_mul_f32_e32 v11, 0x45800000, v10
	v_cndmask_b32_e32 v10, v10, v11, vcc
	v_pk_mul_f32 v[4:5], v[4:5], v[10:11] op_sel_hi:[1,0]
	v_pk_mul_f32 v[2:3], v[2:3], v[10:11] op_sel_hi:[1,0]
	v_pk_mul_f32 v[8:9], v[8:9], v[10:11] op_sel_hi:[1,0]
	v_pk_mul_f32 v[6:7], v[6:7], v[10:11] op_sel_hi:[1,0]
	v_lshl_add_u64 v[10:11], s[8:9], 0, v[194:195]
	v_readlane_b32 s8, v251, 50
	v_lshl_add_u64 v[10:11], v[12:13], 1, v[10:11]
	v_and_b32_e32 v194, 24, v1
	v_readlane_b32 s9, v251, 51
	v_lshl_add_u64 v[10:11], v[10:11], 0, v[194:195]
	v_cvt_pk_bf16_f32 v2, v2, v3
	v_cvt_pk_bf16_f32 v3, v4, v5
	s_andn2_b64 vcc, exec, s[8:9]
	global_store_dwordx2 v[10:11], v[2:3], off
	v_cvt_pk_bf16_f32 v2, v6, v7
	v_cvt_pk_bf16_f32 v3, v8, v9
	global_store_dwordx2 v[10:11], v[2:3], off offset:32
	s_cbranch_vccnz .LBB0_427
	s_waitcnt vmcnt(0)
	v_cmp_eq_u32_e32 vcc, 0, v0
	s_barrier
	s_and_saveexec_b64 s[8:9], vcc
	s_cbranch_execz .LBB0_426
	s_mov_b64 s[36:37], exec
	v_mbcnt_lo_u32_b32 v0, s36, 0
	buffer_wbl2 sc1
	s_waitcnt vmcnt(0)
	s_waitcnt vmcnt(0)
	v_mbcnt_hi_u32_b32 v0, s37, v0
	v_cmp_eq_u32_e32 vcc, 0, v0
	s_and_b64 s[28:29], exec, vcc
	s_mov_b64 exec, s[28:29]
	s_cbranch_execz .LBB0_426
	s_bcnt1_i32_b64 s4, s[36:37]
	v_mov_b32_e32 v0, s4
	global_atomic_add v195, v0, s[0:1]

; #define SCHED __builtin_amdgcn_sched_barrier(0)
; template <class Epi>
; DEV void skinny_item(LAS unsigned char* lds, const bf16_t* __restrict__ A, int lda, const bf16_t* __restrict__ B, int ldb, int K, int mb, int pn, const Epi& epi) {
;     ...
; #pragma unroll 1
;     for (int st = wid; st < nsteps; st += 8) {
;         const int k0 = st * 32;
;         const bf16x8 a = *(const bf16x8*)(ap + k0);
;         bf16x8 b[16];
; #pragma unroll
;         for (int nb = 0; nb < 16; ++nb) b[nb] = *(const bf16x8*)(bp + nb * b16 + k0);
;         SCHED;
; #pragma unroll
;         for (int nb = 0; nb < 16; ++nb) acc[nb] = __builtin_amdgcn_mfma_f32_16x16x32_bf16(b[nb], a, acc[nb], 0, 0, 0);
;         SCHED;
;     }
.LBB0_1224:
	s_movk_i32 s101, 3
	v_ashrrev_i32_e32 v69, 31, v68
	v_lshlrev_b64 v[74:75], 1, v[68:69]
	v_lshl_add_u64 v[138:139], v[64:65], 0, v[74:75]
	v_add_co_u32_e32 v82, vcc, s10, v138
	v_lshl_add_u64 v[76:77], v[66:67], 0, v[74:75]
	s_nop 0
	v_addc_co_u32_e32 v83, vcc, 0, v139, vcc
	v_add_co_u32_e32 v86, vcc, s11, v138
	global_load_dwordx4 v[74:77], v[76:77], off
	s_nop 0
	global_load_dwordx4 v[78:81], v[138:139], off
	v_addc_co_u32_e32 v87, vcc, 0, v139, vcc
	v_add_co_u32_e32 v90, vcc, s12, v138
	global_load_dwordx4 v[82:85], v[82:83], off
	s_nop 0
	global_load_dwordx4 v[86:89], v[86:87], off
	v_addc_co_u32_e32 v91, vcc, 0, v139, vcc
	v_add_co_u32_e32 v94, vcc, s59, v138
	s_nop 1
	v_addc_co_u32_e32 v95, vcc, 0, v139, vcc
	v_add_co_u32_e32 v98, vcc, s13, v138
	global_load_dwordx4 v[90:93], v[90:91], off
	s_nop 0
	global_load_dwordx4 v[94:97], v[94:95], off
	v_addc_co_u32_e32 v99, vcc, 0, v139, vcc
	v_add_co_u32_e32 v102, vcc, s14, v138
	s_nop 1
	v_addc_co_u32_e32 v103, vcc, 0, v139, vcc
	v_add_co_u32_e32 v106, vcc, s15, v138
	global_load_dwordx4 v[98:101], v[98:99], off
	s_nop 0
	global_load_dwordx4 v[102:105], v[102:103], off
	v_addc_co_u32_e32 v107, vcc, 0, v139, vcc
	v_add_co_u32_e32 v110, vcc, s16, v138
	s_nop 1
	v_addc_co_u32_e32 v111, vcc, 0, v139, vcc
	v_add_co_u32_e32 v114, vcc, s17, v138
	global_load_dwordx4 v[106:109], v[106:107], off
	s_nop 0
	global_load_dwordx4 v[110:113], v[110:111], off
	v_addc_co_u32_e32 v115, vcc, 0, v139, vcc
	v_add_co_u32_e32 v118, vcc, s18, v138
	s_nop 1
	v_addc_co_u32_e32 v119, vcc, 0, v139, vcc
	v_add_co_u32_e32 v122, vcc, s19, v138
	global_load_dwordx4 v[114:117], v[114:115], off
	s_nop 0
	global_load_dwordx4 v[118:121], v[118:119], off
	v_addc_co_u32_e32 v123, vcc, 0, v139, vcc
	v_add_co_u32_e32 v126, vcc, s20, v138
	s_nop 1
	v_addc_co_u32_e32 v127, vcc, 0, v139, vcc
	v_add_co_u32_e32 v130, vcc, s21, v138
	global_load_dwordx4 v[122:125], v[122:123], off
	s_nop 0
	global_load_dwordx4 v[126:129], v[126:127], off
	v_addc_co_u32_e32 v131, vcc, 0, v139, vcc
	v_add_co_u32_e32 v134, vcc, s22, v138
	s_nop 1
	v_addc_co_u32_e32 v135, vcc, 0, v139, vcc
	v_add_co_u32_e32 v138, vcc, s23, v138
	global_load_dwordx4 v[130:133], v[130:131], off
	s_nop 0
	global_load_dwordx4 v[134:137], v[134:135], off
	v_addc_co_u32_e32 v139, vcc, 0, v139, vcc
	global_load_dwordx4 v[138:141], v[138:139], off
.Lsk_loop_1224:
	s_cmp_eq_u32 s101, 0
	s_cbranch_scc1 .Lsk_lastA_1224
	s_sub_u32 s101, s101, 1
	v_add_u32_e32 v68, 0x100, v68
	v_ashrrev_i32_e32 v69, 31, v68
	v_lshlrev_b64 v[142:143], 1, v[68:69]
	v_lshl_add_u64 v[232:233], v[64:65], 0, v[142:143]
	v_add_co_u32_e32 v150, vcc, s10, v232
	v_lshl_add_u64 v[144:145], v[66:67], 0, v[142:143]
	s_nop 0
	v_addc_co_u32_e32 v151, vcc, 0, v233, vcc
	v_add_co_u32_e32 v154, vcc, s11, v232
	global_load_dwordx4 v[142:145], v[144:145], off
	s_nop 0
	global_load_dwordx4 v[146:149], v[232:233], off
	v_addc_co_u32_e32 v155, vcc, 0, v233, vcc
	v_add_co_u32_e32 v158, vcc, s12, v232
	global_load_dwordx4 v[150:153], v[150:151], off
	s_nop 0
	global_load_dwordx4 v[154:157], v[154:155], off
	v_addc_co_u32_e32 v159, vcc, 0, v233, vcc
	v_add_co_u32_e32 v162, vcc, s59, v232
	s_nop 1
	v_addc_co_u32_e32 v163, vcc, 0, v233, vcc
	v_add_co_u32_e32 v166, vcc, s13, v232
	global_load_dwordx4 v[158:161], v[158:159], off
	s_nop 0
	global_load_dwordx4 v[162:165], v[162:163], off
	v_addc_co_u32_e32 v167, vcc, 0, v233, vcc
	v_add_co_u32_e32 v170, vcc, s14, v232
	s_nop 1
	v_addc_co_u32_e32 v171, vcc, 0, v233, vcc
	v_add_co_u32_e32 v174, vcc, s15, v232
	global_load_dwordx4 v[166:169], v[166:167], off
	s_nop 0
	global_load_dwordx4 v[170:173], v[170:171], off
	v_addc_co_u32_e32 v175, vcc, 0, v233, vcc
	v_add_co_u32_e32 v178, vcc, s16, v232
	s_nop 1
	v_addc_co_u32_e32 v179, vcc, 0, v233, vcc
	v_add_co_u32_e32 v182, vcc, s17, v232
	global_load_dwordx4 v[174:177], v[174:175], off
	s_nop 0
	global_load_dwordx4 v[178:181], v[178:179], off
	v_addc_co_u32_e32 v183, vcc, 0, v233, vcc
	v_add_co_u32_e32 v212, vcc, s18, v232
	s_nop 1
	v_addc_co_u32_e32 v213, vcc, 0, v233, vcc
	v_add_co_u32_e32 v216, vcc, s19, v232
	global_load_dwordx4 v[182:185], v[182:183], off
	s_nop 0
	global_load_dwordx4 v[212:215], v[212:213], off
	v_addc_co_u32_e32 v217, vcc, 0, v233, vcc
	v_add_co_u32_e32 v220, vcc, s20, v232
	s_nop 1
	v_addc_co_u32_e32 v221, vcc, 0, v233, vcc
	v_add_co_u32_e32 v224, vcc, s21, v232
	global_load_dwordx4 v[216:219], v[216:217], off
	s_nop 0
	global_load_dwordx4 v[220:223], v[220:221], off
	v_addc_co_u32_e32 v225, vcc, 0, v233, vcc
	v_add_co_u32_e32 v228, vcc, s22, v232
	s_nop 1
	v_addc_co_u32_e32 v229, vcc, 0, v233, vcc
	v_add_co_u32_e32 v232, vcc, s23, v232
	global_load_dwordx4 v[224:227], v[224:225], off
	s_nop 0
	global_load_dwordx4 v[228:231], v[228:229], off
	v_addc_co_u32_e32 v233, vcc, 0, v233, vcc
	global_load_dwordx4 v[232:235], v[232:233], off
	s_waitcnt vmcnt(32)
	v_mfma_f32_16x16x32_bf16 v[60:63], v[78:81], v[74:77], v[60:63]
	s_waitcnt vmcnt(31)
	v_mfma_f32_16x16x32_bf16 v[56:59], v[82:85], v[74:77], v[56:59]
	s_waitcnt vmcnt(30)
	v_mfma_f32_16x16x32_bf16 v[52:55], v[86:89], v[74:77], v[52:55]
	s_waitcnt vmcnt(29)
	v_mfma_f32_16x16x32_bf16 v[48:51], v[90:93], v[74:77], v[48:51]
	s_waitcnt vmcnt(28)
	v_mfma_f32_16x16x32_bf16 v[44:47], v[94:97], v[74:77], v[44:47]
	s_waitcnt vmcnt(27)
	v_mfma_f32_16x16x32_bf16 v[40:43], v[98:101], v[74:77], v[40:43]
	s_waitcnt vmcnt(26)
	v_mfma_f32_16x16x32_bf16 v[36:39], v[102:105], v[74:77], v[36:39]
	s_waitcnt vmcnt(25)
	v_mfma_f32_16x16x32_bf16 v[32:35], v[106:109], v[74:77], v[32:35]
	s_waitcnt vmcnt(24)
	v_mfma_f32_16x16x32_bf16 v[28:31], v[110:113], v[74:77], v[28:31]
	s_waitcnt vmcnt(23)
	v_mfma_f32_16x16x32_bf16 v[24:27], v[114:117], v[74:77], v[24:27]
	s_waitcnt vmcnt(22)
	v_mfma_f32_16x16x32_bf16 v[20:23], v[118:121], v[74:77], v[20:23]
	s_waitcnt vmcnt(21)
	v_mfma_f32_16x16x32_bf16 v[16:19], v[122:125], v[74:77], v[16:19]
	s_waitcnt vmcnt(20)
	v_mfma_f32_16x16x32_bf16 v[12:15], v[126:129], v[74:77], v[12:15]
	s_waitcnt vmcnt(19)
	v_mfma_f32_16x16x32_bf16 v[8:11], v[130:133], v[74:77], v[8:11]
	s_waitcnt vmcnt(18)
	v_mfma_f32_16x16x32_bf16 v[4:7], v[134:137], v[74:77], v[4:7]
	s_waitcnt vmcnt(17)
	v_mfma_f32_16x16x32_bf16 v[0:3], v[138:141], v[74:77], v[0:3]
	s_cmp_eq_u32 s101, 0
	s_cbranch_scc1 .Lsk_lastB_1224
; #define SCHED __builtin_amdgcn_sched_barrier(0)
; template <class Epi>
; DEV void skinny_item(LAS unsigned char* lds, const bf16_t* __restrict__ A, int lda, const bf16_t* __restrict__ B, int ldb, int K, int mb, int pn, const Epi& epi) {
;     ...
; #pragma unroll 1
;     for (int st = wid; st < nsteps; st += 8) {
;         const int k0 = st * 32;
;         const bf16x8 a = *(const bf16x8*)(ap + k0);
;         bf16x8 b[16];
; #pragma unroll
;         for (int nb = 0; nb < 16; ++nb) b[nb] = *(const bf16x8*)(bp + nb * b16 + k0);
;         SCHED;
; #pragma unroll
;         for (int nb = 0; nb < 16; ++nb) acc[nb] = __builtin_amdgcn_mfma_f32_16x16x32_bf16(b[nb], a, acc[nb], 0, 0, 0);
;         SCHED;
;     }
	s_sub_u32 s101, s101, 1
	v_add_u32_e32 v68, 0x100, v68
	v_ashrrev_i32_e32 v69, 31, v68
	v_lshlrev_b64 v[74:75], 1, v[68:69]
	v_lshl_add_u64 v[138:139], v[64:65], 0, v[74:75]
	v_add_co_u32_e32 v82, vcc, s10, v138
	v_lshl_add_u64 v[76:77], v[66:67], 0, v[74:75]
	s_nop 0
	v_addc_co_u32_e32 v83, vcc, 0, v139, vcc
	v_add_co_u32_e32 v86, vcc, s11, v138
	global_load_dwordx4 v[74:77], v[76:77], off
	s_nop 0
	global_load_dwordx4 v[78:81], v[138:139], off
	v_addc_co_u32_e32 v87, vcc, 0, v139, vcc
	v_add_co_u32_e32 v90, vcc, s12, v138
	global_load_dwordx4 v[82:85], v[82:83], off
	s_nop 0
	global_load_dwordx4 v[86:89], v[86:87], off
	v_addc_co_u32_e32 v91, vcc, 0, v139, vcc
	v_add_co_u32_e32 v94, vcc, s59, v138
	s_nop 1
	v_addc_co_u32_e32 v95, vcc, 0, v139, vcc
	v_add_co_u32_e32 v98, vcc, s13, v138
	global_load_dwordx4 v[90:93], v[90:91], off
	s_nop 0
	global_load_dwordx4 v[94:97], v[94:95], off
	v_addc_co_u32_e32 v99, vcc, 0, v139, vcc
	v_add_co_u32_e32 v102, vcc, s14, v138
	s_nop 1
	v_addc_co_u32_e32 v103, vcc, 0, v139, vcc
	v_add_co_u32_e32 v106, vcc, s15, v138
	global_load_dwordx4 v[98:101], v[98:99], off
	s_nop 0
	global_load_dwordx4 v[102:105], v[102:103], off
	v_addc_co_u32_e32 v107, vcc, 0, v139, vcc
	v_add_co_u32_e32 v110, vcc, s16, v138
	s_nop 1
	v_addc_co_u32_e32 v111, vcc, 0, v139, vcc
	v_add_co_u32_e32 v114, vcc, s17, v138
	global_load_dwordx4 v[106:109], v[106:107], off
	s_nop 0
	global_load_dwordx4 v[110:113], v[110:111], off
	v_addc_co_u32_e32 v115, vcc, 0, v139, vcc
	v_add_co_u32_e32 v118, vcc, s18, v138
	s_nop 1
	v_addc_co_u32_e32 v119, vcc, 0, v139, vcc
	v_add_co_u32_e32 v122, vcc, s19, v138
	global_load_dwordx4 v[114:117], v[114:115], off
	s_nop 0
	global_load_dwordx4 v[118:121], v[118:119], off
	v_addc_co_u32_e32 v123, vcc, 0, v139, vcc
	v_add_co_u32_e32 v126, vcc, s20, v138
	s_nop 1
	v_addc_co_u32_e32 v127, vcc, 0, v139, vcc
	v_add_co_u32_e32 v130, vcc, s21, v138
	global_load_dwordx4 v[122:125], v[122:123], off
	s_nop 0
	global_load_dwordx4 v[126:129], v[126:127], off
	v_addc_co_u32_e32 v131, vcc, 0, v139, vcc
	v_add_co_u32_e32 v134, vcc, s22, v138
	s_nop 1
	v_addc_co_u32_e32 v135, vcc, 0, v139, vcc
	v_add_co_u32_e32 v138, vcc, s23, v138
	global_load_dwordx4 v[130:133], v[130:131], off
	s_nop 0
	global_load_dwordx4 v[134:137], v[134:135], off
	v_addc_co_u32_e32 v139, vcc, 0, v139, vcc
	global_load_dwordx4 v[138:141], v[138:139], off
	s_waitcnt vmcnt(32)
	v_mfma_f32_16x16x32_bf16 v[60:63], v[146:149], v[142:145], v[60:63]
	s_waitcnt vmcnt(31)
	v_mfma_f32_16x16x32_bf16 v[56:59], v[150:153], v[142:145], v[56:59]
	s_waitcnt vmcnt(30)
	v_mfma_f32_16x16x32_bf16 v[52:55], v[154:157], v[142:145], v[52:55]
	s_waitcnt vmcnt(29)
	v_mfma_f32_16x16x32_bf16 v[48:51], v[158:161], v[142:145], v[48:51]
	s_waitcnt vmcnt(28)
	v_mfma_f32_16x16x32_bf16 v[44:47], v[162:165], v[142:145], v[44:47]
	s_waitcnt vmcnt(27)
	v_mfma_f32_16x16x32_bf16 v[40:43], v[166:169], v[142:145], v[40:43]
	s_waitcnt vmcnt(26)
	v_mfma_f32_16x16x32_bf16 v[36:39], v[170:173], v[142:145], v[36:39]
	s_waitcnt vmcnt(25)
	v_mfma_f32_16x16x32_bf16 v[32:35], v[174:177], v[142:145], v[32:35]
	s_waitcnt vmcnt(24)
	v_mfma_f32_16x16x32_bf16 v[28:31], v[178:181], v[142:145], v[28:31]
	s_waitcnt vmcnt(23)
	v_mfma_f32_16x16x32_bf16 v[24:27], v[182:185], v[142:145], v[24:27]
	s_waitcnt vmcnt(22)
	v_mfma_f32_16x16x32_bf16 v[20:23], v[212:215], v[142:145], v[20:23]
	s_waitcnt vmcnt(21)
	v_mfma_f32_16x16x32_bf16 v[16:19], v[216:219], v[142:145], v[16:19]
	s_waitcnt vmcnt(20)
	v_mfma_f32_16x16x32_bf16 v[12:15], v[220:223], v[142:145], v[12:15]
	s_waitcnt vmcnt(19)
	v_mfma_f32_16x16x32_bf16 v[8:11], v[224:227], v[142:145], v[8:11]
	s_waitcnt vmcnt(18)
	v_mfma_f32_16x16x32_bf16 v[4:7], v[228:231], v[142:145], v[4:7]
	s_waitcnt vmcnt(17)
	v_mfma_f32_16x16x32_bf16 v[0:3], v[232:235], v[142:145], v[0:3]
	s_branch .Lsk_loop_1224

; #define LAS __attribute__((address_space(3)))
; DEV unsigned cvt_pk_bf16(float lo, float hi) { unsigned r; asm("v_cvt_pk_bf16_f32 %0, %1, %2" : "=v"(r) : "v"(lo), "v"(hi)); return r; }
; DEV float bflo(unsigned w) { return __uint_as_float(w << 16); }
; DEV float bfhi(unsigned w) { return __uint_as_float(w & 0xffff0000u); }
; DEV void skinny_reduce(LAS unsigned char* lds, int wid, int lane, const f32x4 (&acc)[16], f32x4& a0, f32x4& a1) {
; #pragma unroll
;     for (int nb = 0; nb < 16; ++nb) *(LAS f32x4*)(lds + ((wid * 16 + nb) * 64 + lane) * 16) = acc[nb];
;     __syncthreads();
;     a0 = (f32x4){0.f, 0.f, 0.f, 0.f}; a1 = a0;
; #pragma unroll
;     for (int w = 0; w < 8; ++w) { a0 += *(const LAS f32x4*)(lds + ((w * 16 + 2 * wid) * 64 + lane) * 16); a1 += *(const LAS f32x4*)(lds + ((w * 16 + 2 * wid + 1) * 64 + lane) * 16); }
;     __syncthreads();
; }
;     DEV void skinny(f32x4 a0, f32x4 a1, int mb, int pn, LAS unsigned char* lds) const {
;         EPI_IDS
;         const int row = TX + mb * 16 + fr, col = pn * 256 + wid * 32 + fq * 4;
;         bf16_t* bp = hb + (size_t)row * D + col;
;         const u32x2 r0 = *(const u32x2*)bp, r1 = *(const u32x2*)(bp + 16);
;         f32x4 v0 = a0, v1 = a1;
;         v0[0] += bflo(r0.x); v0[1] += bfhi(r0.x); v0[2] += bflo(r0.y); v0[3] += bfhi(r0.y);
;         v1[0] += bflo(r1.x); v1[1] += bfhi(r1.x); v1[2] += bflo(r1.y); v1[3] += bfhi(r1.y);
;         *(u32x2*)bp = (u32x2){cvt_pk_bf16(v0[0], v0[1]), cvt_pk_bf16(v0[2], v0[3])};
;         *(u32x2*)(bp + 16) = (u32x2){cvt_pk_bf16(v1[0], v1[1]), cvt_pk_bf16(v1[2], v1[3])};
;         float s = ((v0[0] * v0[0] + v0[1] * v0[1]) + (v0[2] * v0[2] + v0[3] * v0[3])) + ((v1[0] * v1[0] + v1[1] * v1[1]) + (v1[2] * v1[2] + v1[3] * v1[3]));
;         s += __shfl_xor(s, 16); s += __shfl_xor(s, 32);
;         LAS float* ex = (LAS float*)(lds + LDS_EX);
;         if (fq == 0) ex[fr * 8 + wid] = s;
.Lsk_done_1224:
	s_or_b64 exec, exec, s[36:37]
.LBB0_1226:
	s_or_b64 exec, exec, s[8:9]
	v_lshlrev_b32_e32 v65, 4, v71
	v_lshlrev_b32_e32 v64, 14, v70
	v_and_b32_e32 v65, 0x3f0, v65
	v_add3_u32 v64, 0, v64, v65
	ds_write_b128 v64, v[60:63]
	ds_write_b128 v64, v[56:59] offset:1024
	ds_write_b128 v64, v[52:55] offset:2048
	ds_write_b128 v64, v[48:51] offset:3072
	ds_write_b128 v64, v[44:47] offset:4096
	ds_write_b128 v64, v[40:43] offset:5120
	ds_write_b128 v64, v[36:39] offset:6144
	ds_write_b128 v64, v[32:35] offset:7168
	ds_write_b128 v64, v[28:31] offset:8192
	ds_write_b128 v64, v[24:27] offset:9216
	ds_write_b128 v64, v[20:23] offset:10240
	ds_write_b128 v64, v[16:19] offset:11264
	ds_write_b128 v64, v[12:15] offset:12288
	ds_write_b128 v64, v[8:11] offset:13312
	ds_write_b128 v64, v[4:7] offset:14336
	ds_write_b128 v64, v[0:3] offset:15360
	v_lshlrev_b32_e32 v0, 11, v70
	v_add3_u32 v12, 0, v0, v65
	s_waitcnt lgkmcnt(0)
	s_barrier
	ds_read_b128 v[0:3], v12
	s_waitcnt lgkmcnt(0)
	v_pk_add_f32 v[4:5], v[2:3], 0 op_sel_hi:[1,0]
	v_pk_add_f32 v[6:7], v[0:1], 0 op_sel_hi:[1,0]
	ds_read_b128 v[0:3], v12 offset:1024
	s_waitcnt lgkmcnt(0)
	v_pk_add_f32 v[8:9], v[2:3], 0 op_sel_hi:[1,0]
	v_pk_add_f32 v[10:11], v[0:1], 0 op_sel_hi:[1,0]
	ds_read_b128 v[0:3], v12 offset:16384
	s_waitcnt lgkmcnt(0)
	v_pk_add_f32 v[4:5], v[4:5], v[2:3]
	v_pk_add_f32 v[6:7], v[6:7], v[0:1]
	ds_read_b128 v[0:3], v12 offset:17408
	s_waitcnt lgkmcnt(0)
	v_pk_add_f32 v[8:9], v[8:9], v[2:3]
	v_pk_add_f32 v[10:11], v[10:11], v[0:1]
	ds_read_b128 v[0:3], v12 offset:32768
	s_waitcnt lgkmcnt(0)
	v_pk_add_f32 v[4:5], v[4:5], v[2:3]
	v_pk_add_f32 v[6:7], v[6:7], v[0:1]
	ds_read_b128 v[0:3], v12 offset:33792
	s_waitcnt lgkmcnt(0)
	v_pk_add_f32 v[8:9], v[8:9], v[2:3]
	v_pk_add_f32 v[10:11], v[10:11], v[0:1]
	ds_read_b128 v[0:3], v12 offset:49152
	s_waitcnt lgkmcnt(0)
	v_pk_add_f32 v[4:5], v[4:5], v[2:3]
	v_pk_add_f32 v[6:7], v[6:7], v[0:1]
	ds_read_b128 v[0:3], v12 offset:50176
	s_waitcnt lgkmcnt(0)
	v_pk_add_f32 v[10:11], v[10:11], v[0:1]
	v_add_u32_e32 v0, 0x10000, v12
	v_pk_add_f32 v[8:9], v[8:9], v[2:3]
	ds_read_b128 v[0:3], v0
	s_waitcnt lgkmcnt(0)
	v_pk_add_f32 v[6:7], v[6:7], v[0:1]
	v_add_u32_e32 v0, 0x10400, v12
	v_pk_add_f32 v[4:5], v[4:5], v[2:3]
	ds_read_b128 v[0:3], v0
	s_waitcnt lgkmcnt(0)
	v_pk_add_f32 v[10:11], v[10:11], v[0:1]
	v_add_u32_e32 v0, 0x14000, v12
	v_pk_add_f32 v[8:9], v[8:9], v[2:3]
	ds_read_b128 v[0:3], v0
	s_waitcnt lgkmcnt(0)
	v_pk_add_f32 v[6:7], v[6:7], v[0:1]
	v_add_u32_e32 v0, 0x14400, v12
	v_pk_add_f32 v[4:5], v[4:5], v[2:3]
	ds_read_b128 v[0:3], v0
	s_waitcnt lgkmcnt(0)
	v_pk_add_f32 v[10:11], v[10:11], v[0:1]
	v_add_u32_e32 v0, 0x18000, v12
	v_pk_add_f32 v[8:9], v[8:9], v[2:3]
	ds_read_b128 v[0:3], v0
	s_waitcnt lgkmcnt(0)
	v_pk_add_f32 v[6:7], v[6:7], v[0:1]
	v_add_u32_e32 v0, 0x18400, v12
	v_pk_add_f32 v[4:5], v[4:5], v[2:3]
	ds_read_b128 v[0:3], v0
	s_waitcnt lgkmcnt(0)
	v_pk_add_f32 v[10:11], v[10:11], v[0:1]
	v_add_u32_e32 v0, 0x1c000, v12
	v_pk_add_f32 v[8:9], v[8:9], v[2:3]
	ds_read_b128 v[0:3], v0
	s_waitcnt lgkmcnt(0)
	v_pk_add_f32 v[6:7], v[6:7], v[0:1]
	v_add_u32_e32 v0, 0x1c400, v12
	v_pk_add_f32 v[4:5], v[4:5], v[2:3]
	ds_read_b128 v[0:3], v0
	s_waitcnt lgkmcnt(0)
	s_barrier
	v_pk_add_f32 v[10:11], v[10:11], v[0:1]
	v_mov_b32_e32 v0, v188
	v_pk_add_f32 v[8:9], v[8:9], v[2:3]
	s_nop 0
	v_ashrrev_i32_e32 v1, 6, v0
	v_and_b32_e32 v2, 15, v0
	v_bfe_u32 v18, v0, 4, 2
	v_or_b32_e32 v194, s1, v2
	v_lshl_add_u32 v3, v1, 5, s7
	v_lshl_or_b32 v12, v18, 2, v3
	v_lshlrev_b64 v[14:15], 11, v[194:195]
	v_lshl_add_u64 v[14:15], s[72:73], 0, v[14:15]
	v_ashrrev_i32_e32 v13, 31, v12
	v_lshl_add_u64 v[12:13], v[12:13], 1, v[14:15]
	global_load_dwordx2 v[14:15], v[12:13], off
	global_load_dwordx2 v[16:17], v[12:13], off offset:32
	s_waitcnt vmcnt(1)
	v_lshlrev_b32_e32 v3, 16, v14
	v_add_f32_e32 v3, v6, v3
	v_and_b32_e32 v6, 0xffff0000, v14
	v_add_f32_e32 v6, v7, v6
	v_lshlrev_b32_e32 v7, 16, v15
	v_add_f32_e32 v7, v4, v7
	v_and_b32_e32 v4, 0xffff0000, v15
	v_add_f32_e32 v14, v5, v4
	s_waitcnt vmcnt(0)
	v_lshlrev_b32_e32 v4, 16, v16
	v_add_f32_e32 v10, v10, v4
	v_and_b32_e32 v4, 0xffff0000, v16
	v_add_f32_e32 v11, v11, v4
	v_lshlrev_b32_e32 v4, 16, v17
	v_add_f32_e32 v8, v8, v4
	v_and_b32_e32 v4, 0xffff0000, v17
	v_add_f32_e32 v9, v9, v4
	v_cvt_pk_bf16_f32 v4, v3, v6
	v_cvt_pk_bf16_f32 v5, v7, v14
	global_store_dwordx2 v[12:13], v[4:5], off
	v_cvt_pk_bf16_f32 v4, v10, v11
	v_cvt_pk_bf16_f32 v5, v8, v9
	global_store_dwordx2 v[12:13], v[4:5], off offset:32
	v_mul_f32_e32 v4, v6, v6
	v_fmac_f32_e32 v4, v3, v3
	v_mul_f32_e32 v3, v14, v14
	v_fmac_f32_e32 v3, v7, v7
	v_add_f32_e32 v3, v4, v3
	v_mul_f32_e32 v4, v11, v11
	v_mul_f32_e32 v5, v9, v9
	v_fmac_f32_e32 v4, v10, v10
	v_fmac_f32_e32 v5, v8, v8
	v_add_f32_e32 v4, v4, v5
	v_and_b32_e32 v5, 64, v207
	v_add_f32_e32 v3, v3, v4
	v_xor_b32_e32 v4, 16, v207
	v_add_u32_e32 v5, 64, v5
	v_cmp_lt_i32_e32 vcc, v4, v5
	s_nop 1
	v_cndmask_b32_e32 v4, v207, v4, vcc
	v_lshlrev_b32_e32 v4, 2, v4
	ds_bpermute_b32 v4, v4, v3
	s_waitcnt lgkmcnt(0)
	v_add_f32_e32 v3, v3, v4
	v_xor_b32_e32 v4, 32, v207
	v_cmp_lt_i32_e32 vcc, v4, v5
	s_nop 1
	v_cndmask_b32_e32 v4, v207, v4, vcc
	v_lshlrev_b32_e32 v4, 2, v4
	ds_bpermute_b32 v4, v4, v3
	v_cmp_eq_u32_e32 vcc, 0, v18
	s_and_saveexec_b64 s[8:9], vcc
	s_cbranch_execz .LBB0_1228
	v_lshlrev_b32_e32 v2, 5, v2
	s_add_i32 s7, 0, 0x20000
	v_lshlrev_b32_e32 v1, 2, v1
	s_waitcnt lgkmcnt(0)
	v_add_f32_e32 v3, v3, v4
	v_add3_u32 v1, s7, v2, v1
	ds_write_b32 v1, v3
